# prep phase: V-row loads issued with K-row loads in KV-layout items; memkv_ops loads prefetched; cmp_stage2 w2 LDS fill loads issued together
# speedup vs baseline: 1.0111x; 1.0111x over previous
; #define LAS __attribute__((address_space(3)))
; #define LDS_WAIT() asm volatile("s_waitcnt lgkmcnt(0)" ::: "memory")
; __device__ __forceinline__ void prep_items(const Ctx& C, int l, int w0, int nw) {
;     ...
;                 for (int q = 0; q < 4; ++q) {
;                     const int r = (lane >> 3) + 8 * q, c = lane & 7;
;                     const bf16_t* row = P + (tokb + r) * PP;
;                     u32x4 kv = *(const u32x4*)(row + kc + 8 * c);
;                     if (c < 2) {
;                         const u32x4 pv = *(const u32x4*)(row + kc + 8 * (c ^ 1));
;                         const float* rt = rope + (tokb + r) * 16;
;                         const f32x4 ca = *(const f32x4*)rt, cb2 = *(const f32x4*)(rt + 4), sa = *(const f32x4*)(rt + 8), sb = *(const f32x4*)(rt + 12);
;                         const float cs[8] = {ca.x, ca.y, ca.z, ca.w, cb2.x, cb2.y, cb2.z, cb2.w}, sn[8] = {sa.x, sa.y, sa.z, sa.w, sb.x, sb.y, sb.z, sb.w};
;                         const float mv[8] = {bf_lo(kv.x), bf_hi(kv.x), bf_lo(kv.y), bf_hi(kv.y), bf_lo(kv.z), bf_hi(kv.z), bf_lo(kv.w), bf_hi(kv.w)};
;                         const float pp[8] = {bf_lo(pv.x), bf_hi(pv.x), bf_lo(pv.y), bf_hi(pv.y), bf_lo(pv.z), bf_hi(pv.z), bf_lo(pv.w), bf_hi(pv.w)};
;                         const float sg = (c == 0) ? -1.f : 1.f; float o[8];
; #pragma unroll
;                         for (int e = 0; e < 8; ++e) o[e] = mv[e] * cs[e] + sg * pp[e] * sn[e];
;                         kv.x = cvt_pk_bf16(o[0], o[1]); kv.y = cvt_pk_bf16(o[2], o[3]); kv.z = cvt_pk_bf16(o[4], o[5]); kv.w = cvt_pk_bf16(o[6], o[7]);
;                     }
;                     if (which == 0)
;                         *(u32x4*)(kop + ((size_t)(((bg * 512 + tile) * 2 + ((r >> 2) & 1)) * 2 + (c >> 2)) * 64 + ((r >> 3) * 4 + (r & 3)) + 16 * (c & 3)) * 8) = kv;
;                     else
;                         *(u32x4*)(kop + ((size_t)((bg * 512 + tile) * 4 + (c >> 1)) * 64 + pi32(r) + 32 * (c & 1)) * 8) = kv;
;                     const u32x4 vv = *(const u32x4*)(row + vc + 8 * c);
;                     *(LAS u32x4*)(vt + r * 72 + 8 * c) = vv;
;                 }
;                 LDS_WAIT();
; #pragma unroll
;                 for (int o4 = 0; o4 < 4; ++o4) {
;                     if (which == 0) {
;                         const LAS bf16_t* sp = vt + (8 * (lane >> 4)) * 72 + 16 * o4 + (lane & 15);
.LBB0_479:
	s_or_b64 exec, exec, s[12:13]
	v_or_b32_e32 v48, v48, v40
	v_lshl_add_u64 v[2:3], v[48:49], 4, s[34:35]
	s_waitcnt vmcnt(0)
	global_store_dwordx4 v[2:3], v[6:9], off
	s_lshl_b32 s2, s72, 11
	s_lshl_b32 s3, s73, 2
	s_or_b32 s2, s2, s3
	s_ashr_i32 s3, s2, 31
	s_lshl_b64 s[10:11], s[2:3], 10
	v_lshl_add_u64 v[6:7], v[44:45], 0, s[10:11]
	s_or_b32 s10, s2, 1
	s_ashr_i32 s11, s10, 31
	s_lshl_b64 s[10:11], s[10:11], 10
	s_add_i32 s9, s9, s46
	s_add_i32 s6, s6, s27
	ds_write_b128 v23, v[106:109] offset:3456
	s_waitcnt lgkmcnt(0)
	ds_read_u16 v0, v17
	ds_read_u16 v2, v17 offset:144
	s_waitcnt lgkmcnt(0)
	v_lshl_or_b32 v2, v2, 16, v0
	ds_read_u16 v0, v17 offset:288
	ds_read_u16 v3, v17 offset:432
	s_waitcnt lgkmcnt(0)
	v_lshl_or_b32 v3, v3, 16, v0
	ds_read_u16 v0, v17 offset:576
	ds_read_u16 v4, v17 offset:720
	s_waitcnt lgkmcnt(0)
	v_lshl_or_b32 v4, v4, 16, v0
	ds_read_u16 v0, v17 offset:864
	ds_read_u16 v5, v17 offset:1008
	s_waitcnt lgkmcnt(0)
	v_lshl_or_b32 v5, v5, 16, v0
	global_store_dwordx4 v[6:7], v[2:5], off
	ds_read_u16 v0, v17 offset:64
	ds_read_u16 v2, v17 offset:208
	v_lshl_add_u64 v[6:7], v[44:45], 0, s[10:11]
	s_or_b32 s10, s2, 2
	s_ashr_i32 s11, s10, 31
	s_lshl_b64 s[10:11], s[10:11], 10
	s_waitcnt lgkmcnt(0)
	v_lshl_or_b32 v2, v2, 16, v0
	ds_read_u16 v0, v17 offset:352
	ds_read_u16 v3, v17 offset:496
	s_or_b32 s2, s2, 3
	s_ashr_i32 s3, s2, 31
	s_lshl_b64 s[2:3], s[2:3], 10
	s_cmpk_lt_i32 s9, 0x800
	s_waitcnt lgkmcnt(0)
	v_lshl_or_b32 v3, v3, 16, v0
	ds_read_u16 v0, v17 offset:640
	ds_read_u16 v4, v17 offset:784
	s_waitcnt lgkmcnt(0)
	v_lshl_or_b32 v4, v4, 16, v0
	ds_read_u16 v0, v17 offset:928
	ds_read_u16 v5, v17 offset:1072
	s_waitcnt lgkmcnt(0)
	v_lshl_or_b32 v5, v5, 16, v0
	global_store_dwordx4 v[6:7], v[2:5], off
	ds_read_u16 v0, v17 offset:2304
	ds_read_u16 v2, v17 offset:2448
	v_lshl_add_u64 v[6:7], v[44:45], 0, s[10:11]
	s_waitcnt lgkmcnt(0)
	v_lshl_or_b32 v2, v2, 16, v0
	ds_read_u16 v0, v17 offset:2592
	ds_read_u16 v3, v17 offset:2736
	s_waitcnt lgkmcnt(0)
	v_lshl_or_b32 v3, v3, 16, v0
	ds_read_u16 v0, v17 offset:2880
	ds_read_u16 v4, v17 offset:3024
	s_waitcnt lgkmcnt(0)
	v_lshl_or_b32 v4, v4, 16, v0
	ds_read_u16 v0, v17 offset:3168
	ds_read_u16 v5, v17 offset:3312
	s_waitcnt lgkmcnt(0)
	v_lshl_or_b32 v5, v5, 16, v0
	global_store_dwordx4 v[6:7], v[2:5], off
	ds_read_u16 v0, v17 offset:2368
	ds_read_u16 v2, v17 offset:2512
	v_lshl_add_u64 v[6:7], v[44:45], 0, s[2:3]
	s_waitcnt lgkmcnt(0)
	v_lshl_or_b32 v2, v2, 16, v0
	ds_read_u16 v0, v17 offset:2656
	ds_read_u16 v3, v17 offset:2800
	s_waitcnt lgkmcnt(0)
	v_lshl_or_b32 v3, v3, 16, v0
	ds_read_u16 v0, v17 offset:2944
	ds_read_u16 v4, v17 offset:3088
	s_waitcnt lgkmcnt(0)
	v_lshl_or_b32 v4, v4, 16, v0
	ds_read_u16 v0, v17 offset:3232
	ds_read_u16 v5, v17 offset:3376
	s_waitcnt lgkmcnt(0)
	v_lshl_or_b32 v5, v5, 16, v0
	global_store_dwordx4 v[6:7], v[2:5], off
	s_waitcnt lgkmcnt(0)
	s_cbranch_scc0 .LBB0_512
.LBB0_480:
	s_ashr_i32 s2, s9, 10
	s_and_b32 s73, s9, 0x1ff
	s_ashr_i32 s3, s2, 31
	s_ashr_i32 s72, s9, 9
	s_lshl_b64 s[12:13], s[2:3], 14
	s_lshl_b32 s2, s73, 5
	s_or_b32 s12, s12, s2
	s_lshl_b32 s2, s72, 7
	s_and_b32 s2, s2, 0x80
	s_add_u32 s16, s30, s2
	s_addc_u32 s17, s31, 0
	s_add_u32 s18, s16, 0x1200
	s_addc_u32 s19, s17, 0
	v_or_b32_e32 v62, s12, v10
	v_mov_b64_e32 v[2:3], s[18:19]
	v_mad_u64_u32 v[2:3], s[2:3], v62, s67, v[2:3]
	v_mad_i32_i24 v3, s13, v233, v3
	v_lshlrev_b32_e32 v0, 1, v12
	v_lshl_add_u64 v[50:51], v[2:3], 0, v[0:1]
	global_load_dwordx4 v[6:9], v[50:51], off
	global_load_dwordx4 v[102:105], v[50:51], off offset:256
	v_mov_b32_e32 v63, s13
	s_and_saveexec_b64 s[2:3], vcc
	s_xor_b64 s[2:3], exec, s[2:3]
	s_or_saveexec_b64 s[78:79], s[2:3]
	v_lshlrev_b64 v[4:5], 6, v[62:63]
	v_lshlrev_b32_e32 v46, 1, v14
	v_lshl_add_u64 v[48:49], s[22:23], 0, v[4:5]
	s_xor_b64 exec, exec, s[78:79]
	s_cbranch_execz .LBB0_484
	v_mov_b32_e32 v47, v1
	v_lshl_add_u64 v[2:3], v[2:3], 0, v[46:47]
	global_load_dwordx4 v[52:55], v[2:3], off
	global_load_dwordx4 v[56:59], v[48:49], off offset:16
	s_nop 0
	global_load_dwordx4 v[2:5], v[48:49], off offset:48
	global_load_dwordx4 v[64:67], v[48:49], off
	global_load_dwordx4 v[70:73], v[48:49], off offset:32
	s_waitcnt vmcnt(5)
	v_lshlrev_b32_e32 v76, 16, v7
	v_and_b32_e32 v78, 0xffff0000, v7
	v_lshlrev_b32_e32 v60, 16, v6
	v_and_b32_e32 v74, 0xffff0000, v6
	v_lshlrev_b32_e32 v82, 16, v9
	v_and_b32_e32 v6, 0xffff0000, v9
	v_lshlrev_b32_e32 v80, 16, v8
	v_and_b32_e32 v8, 0xffff0000, v8
	s_waitcnt vmcnt(4)
	v_lshlrev_b32_e32 v7, 16, v52
	v_and_b32_e32 v9, 0xffff0000, v52
	v_lshlrev_b32_e32 v25, 16, v53
	v_and_b32_e32 v27, 0xffff0000, v53
	v_and_b32_e32 v31, 0xffff0000, v54
	v_cndmask_b32_e64 v61, v7, -v7, s[0:1]
	s_waitcnt vmcnt(1)
	v_mov_b32_e32 v52, v64
	s_waitcnt vmcnt(0)
	v_mov_b32_e32 v53, v70
	v_lshlrev_b32_e32 v33, 16, v55
	v_and_b32_e32 v35, 0xffff0000, v55
	v_pk_mul_f32 v[52:53], v[52:53], v[60:61]
	v_cndmask_b32_e64 v75, v9, -v9, s[0:1]
	v_mov_b32_e32 v70, v65
	v_cndmask_b32_e64 v77, v25, -v25, s[0:1]
	v_mov_b32_e32 v60, v66
	v_mov_b32_e32 v61, v72
	v_cndmask_b32_e64 v79, v27, -v27, s[0:1]
	v_mov_b32_e32 v72, v67
	v_mov_b32_e32 v67, v2
	v_cndmask_b32_e64 v9, v31, -v31, s[0:1]
	v_mov_b32_e32 v2, v57
	v_lshlrev_b32_e32 v29, 16, v54
	v_pk_mul_f32 v[54:55], v[70:71], v[74:75]
	v_pk_mul_f32 v[60:61], v[60:61], v[76:77]
	v_pk_mul_f32 v[64:65], v[72:73], v[78:79]
	v_pk_mul_f32 v[2:3], v[2:3], v[8:9]
	v_cndmask_b32_e64 v83, v33, -v33, s[0:1]
	v_mov_b32_e32 v8, v58
	v_mov_b32_e32 v9, v4
	v_cndmask_b32_e64 v7, v35, -v35, s[0:1]
	v_mov_b32_e32 v4, v59
	v_cndmask_b32_e64 v81, v29, -v29, s[0:1]
	v_mov_b32_e32 v66, v56
	v_pk_mul_f32 v[56:57], v[8:9], v[82:83]
	v_pk_mul_f32 v[4:5], v[4:5], v[6:7]
	v_mov_b32_e32 v6, v52
	v_mov_b32_e32 v7, v54
	v_mov_b32_e32 v54, v53
	v_mov_b32_e32 v8, v60
	v_mov_b32_e32 v9, v64
	v_mov_b32_e32 v64, v61
	v_pk_mul_f32 v[66:67], v[66:67], v[80:81]
	v_pk_add_f32 v[6:7], v[6:7], v[54:55]
	v_pk_add_f32 v[8:9], v[8:9], v[64:65]
	v_cvt_pk_bf16_f32 v6, v6, v7
	v_cvt_pk_bf16_f32 v7, v8, v9
	v_mov_b32_e32 v8, v66
	v_mov_b32_e32 v9, v2
	v_mov_b32_e32 v2, v67
	v_pk_add_f32 v[2:3], v[8:9], v[2:3]
	s_nop 0
	v_cvt_pk_bf16_f32 v8, v2, v3
	v_mov_b32_e32 v2, v56
	v_mov_b32_e32 v3, v4
	v_mov_b32_e32 v4, v57
	v_pk_add_f32 v[2:3], v[2:3], v[4:5]
	s_nop 0
	v_cvt_pk_bf16_f32 v9, v2, v3
; #define LAS __attribute__((address_space(3)))
; __device__ __forceinline__ unsigned cvt_pk_bf16(float lo, float hi) { f32x2_t v = {lo, hi}; bf16x2_t b = __builtin_convertvector(v, bf16x2_t); return __builtin_bit_cast(unsigned, b); }
; __device__ __forceinline__ float bf_lo(unsigned u) { return __uint_as_float(u << 16); }
; __device__ __forceinline__ void prep_items(const Ctx& C, int l, int w0, int nw) {
;     ...
;                 for (int q = 0; q < 4; ++q) {
;                     const int r = (lane >> 3) + 8 * q, c = lane & 7;
;                     const bf16_t* row = P + (tokb + r) * PP;
;                     u32x4 kv = *(const u32x4*)(row + kc + 8 * c);
;                     if (c < 2) {
;                         const u32x4 pv = *(const u32x4*)(row + kc + 8 * (c ^ 1));
;                         const float* rt = rope + (tokb + r) * 16;
;                         const f32x4 ca = *(const f32x4*)rt, cb2 = *(const f32x4*)(rt + 4), sa = *(const f32x4*)(rt + 8), sb = *(const f32x4*)(rt + 12);
;                         const float cs[8] = {ca.x, ca.y, ca.z, ca.w, cb2.x, cb2.y, cb2.z, cb2.w}, sn[8] = {sa.x, sa.y, sa.z, sa.w, sb.x, sb.y, sb.z, sb.w};
;                         const float mv[8] = {bf_lo(kv.x), bf_hi(kv.x), bf_lo(kv.y), bf_hi(kv.y), bf_lo(kv.z), bf_hi(kv.z), bf_lo(kv.w), bf_hi(kv.w)};
;                         const float pp[8] = {bf_lo(pv.x), bf_hi(pv.x), bf_lo(pv.y), bf_hi(pv.y), bf_lo(pv.z), bf_hi(pv.z), bf_lo(pv.w), bf_hi(pv.w)};
;                         const float sg = (c == 0) ? -1.f : 1.f; float o[8];
; #pragma unroll
;                         for (int e = 0; e < 8; ++e) o[e] = mv[e] * cs[e] + sg * pp[e] * sn[e];
;                         kv.x = cvt_pk_bf16(o[0], o[1]); kv.y = cvt_pk_bf16(o[2], o[3]); kv.z = cvt_pk_bf16(o[4], o[5]); kv.w = cvt_pk_bf16(o[6], o[7]);
;                     }
;                     if (which == 0)
;                         *(u32x4*)(kop + ((size_t)(((bg * 512 + tile) * 2 + ((r >> 2) & 1)) * 2 + (c >> 2)) * 64 + ((r >> 3) * 4 + (r & 3)) + 16 * (c & 3)) * 8) = kv;
;                     else
;                         *(u32x4*)(kop + ((size_t)((bg * 512 + tile) * 4 + (c >> 1)) * 64 + pi32(r) + 32 * (c & 1)) * 8) = kv;
;                     const u32x4 vv = *(const u32x4*)(row + vc + 8 * c);
;                     *(LAS u32x4*)(vt + r * 72 + 8 * c) = vv;
;                 }
.LBB0_484:
	s_or_b64 exec, exec, s[78:79]
	v_add_u32_e32 v2, s6, v19
	v_ashrrev_i32_e32 v3, 31, v2
	v_lshlrev_b64 v[64:65], 6, v[2:3]
	v_or_b32_e32 v64, v64, v20
	v_or_b32_e32 v2, v64, v18
	v_mov_b32_e32 v3, v65
	v_lshl_add_u64 v[2:3], v[2:3], 4, s[24:25]
	s_waitcnt vmcnt(0)
	global_store_dwordx4 v[2:3], v[6:9], off
	v_or_b32_e32 v54, s12, v22
	s_mul_i32 s74, s13, 0x1c00
	v_mov_b32_e32 v55, s13
	ds_write_b128 v23, v[102:105]
	v_mov_b64_e32 v[2:3], s[18:19]
	v_mad_u64_u32 v[2:3], s[2:3], v54, s67, v[2:3]
	v_add_u32_e32 v3, s74, v3
	v_lshl_add_u64 v[52:53], v[2:3], 0, v[0:1]
	global_load_dwordx4 v[6:9], v[52:53], off
	global_load_dwordx4 v[106:109], v[52:53], off offset:256
	s_and_saveexec_b64 s[2:3], vcc
	s_xor_b64 s[2:3], exec, s[2:3]
	s_or_saveexec_b64 s[78:79], s[2:3]
	v_lshlrev_b64 v[4:5], 6, v[54:55]
	v_lshl_add_u64 v[50:51], s[22:23], 0, v[4:5]
	s_xor_b64 exec, exec, s[78:79]
	s_cbranch_execz .LBB0_488
	v_mov_b32_e32 v47, v1
	v_lshl_add_u64 v[2:3], v[2:3], 0, v[46:47]
	global_load_dwordx4 v[56:59], v[2:3], off
	global_load_dwordx4 v[70:73], v[50:51], off offset:16
	s_nop 0
	global_load_dwordx4 v[2:5], v[50:51], off offset:48
	global_load_dwordx4 v[74:77], v[50:51], off
	global_load_dwordx4 v[78:81], v[50:51], off offset:32
	s_waitcnt vmcnt(5)
	v_lshlrev_b32_e32 v82, 16, v7
	v_and_b32_e32 v84, 0xffff0000, v7
	v_lshlrev_b32_e32 v60, 16, v6
	v_and_b32_e32 v66, 0xffff0000, v6
	v_lshlrev_b32_e32 v88, 16, v9
	v_and_b32_e32 v6, 0xffff0000, v9
	v_lshlrev_b32_e32 v86, 16, v8
	v_and_b32_e32 v8, 0xffff0000, v8
	s_waitcnt vmcnt(4)
	v_lshlrev_b32_e32 v7, 16, v56
	v_and_b32_e32 v9, 0xffff0000, v56
	v_lshlrev_b32_e32 v25, 16, v57
	v_and_b32_e32 v27, 0xffff0000, v57
	v_and_b32_e32 v31, 0xffff0000, v58
	v_cndmask_b32_e64 v61, v7, -v7, s[0:1]
	s_waitcnt vmcnt(1)
	v_mov_b32_e32 v56, v74
	s_waitcnt vmcnt(0)
	v_mov_b32_e32 v57, v78
	v_lshlrev_b32_e32 v33, 16, v59
	v_and_b32_e32 v35, 0xffff0000, v59
	v_pk_mul_f32 v[56:57], v[56:57], v[60:61]
	v_cndmask_b32_e64 v67, v9, -v9, s[0:1]
	v_mov_b32_e32 v78, v75
	v_cndmask_b32_e64 v83, v25, -v25, s[0:1]
	v_mov_b32_e32 v60, v76
	v_mov_b32_e32 v61, v80
	v_cndmask_b32_e64 v85, v27, -v27, s[0:1]
	v_mov_b32_e32 v80, v77
	v_mov_b32_e32 v75, v2
	v_cndmask_b32_e64 v9, v31, -v31, s[0:1]
	v_mov_b32_e32 v2, v71
	v_lshlrev_b32_e32 v29, 16, v58
	v_pk_mul_f32 v[58:59], v[78:79], v[66:67]
	v_pk_mul_f32 v[60:61], v[60:61], v[82:83]
	v_pk_mul_f32 v[66:67], v[80:81], v[84:85]
	v_pk_mul_f32 v[2:3], v[2:3], v[8:9]
	v_cndmask_b32_e64 v89, v33, -v33, s[0:1]
	v_mov_b32_e32 v8, v72
	v_mov_b32_e32 v9, v4
	v_cndmask_b32_e64 v7, v35, -v35, s[0:1]
	v_mov_b32_e32 v4, v73
	v_cndmask_b32_e64 v87, v29, -v29, s[0:1]
	v_mov_b32_e32 v74, v70
	v_pk_mul_f32 v[70:71], v[8:9], v[88:89]
	v_pk_mul_f32 v[4:5], v[4:5], v[6:7]
	v_mov_b32_e32 v6, v56
	v_mov_b32_e32 v7, v58
	v_mov_b32_e32 v58, v57
	v_mov_b32_e32 v8, v60
	v_mov_b32_e32 v9, v66
	v_mov_b32_e32 v66, v61
	v_pk_mul_f32 v[74:75], v[74:75], v[86:87]
	v_pk_add_f32 v[6:7], v[6:7], v[58:59]
	v_pk_add_f32 v[8:9], v[8:9], v[66:67]
	v_cvt_pk_bf16_f32 v6, v6, v7
	v_cvt_pk_bf16_f32 v7, v8, v9
	v_mov_b32_e32 v8, v74
	v_mov_b32_e32 v9, v2
	v_mov_b32_e32 v2, v75
	v_pk_add_f32 v[2:3], v[8:9], v[2:3]
	s_nop 0
	v_cvt_pk_bf16_f32 v8, v2, v3
	v_mov_b32_e32 v2, v70
	v_mov_b32_e32 v3, v4
	v_mov_b32_e32 v4, v71
	v_pk_add_f32 v[2:3], v[2:3], v[4:5]
	s_nop 0
	v_cvt_pk_bf16_f32 v9, v2, v3
.LBB0_488:
	s_or_b64 exec, exec, s[78:79]
	v_or_b32_e32 v2, v64, v24
	v_mov_b32_e32 v3, v65
	v_lshl_add_u64 v[2:3], v[2:3], 4, s[24:25]
	s_waitcnt vmcnt(0)
	global_store_dwordx4 v[2:3], v[6:9], off
	v_or_b32_e32 v56, s12, v26
	v_mov_b32_e32 v57, s13
	ds_write_b128 v23, v[106:109] offset:1152
	v_mov_b64_e32 v[2:3], s[18:19]
	v_mad_u64_u32 v[2:3], s[2:3], v56, s67, v[2:3]
	v_add_u32_e32 v3, s74, v3
	v_lshl_add_u64 v[58:59], v[2:3], 0, v[0:1]
	global_load_dwordx4 v[6:9], v[58:59], off
	global_load_dwordx4 v[102:105], v[58:59], off offset:256
	s_and_saveexec_b64 s[2:3], vcc
	s_xor_b64 s[2:3], exec, s[2:3]
	s_or_saveexec_b64 s[78:79], s[2:3]
	v_lshlrev_b64 v[4:5], 6, v[56:57]
	v_lshl_add_u64 v[52:53], s[22:23], 0, v[4:5]
	s_xor_b64 exec, exec, s[78:79]
	s_cbranch_execz .LBB0_492
	v_mov_b32_e32 v47, v1
	v_lshl_add_u64 v[2:3], v[2:3], 0, v[46:47]
	global_load_dwordx4 v[70:73], v[2:3], off
	global_load_dwordx4 v[74:77], v[52:53], off offset:16
	s_nop 0
	global_load_dwordx4 v[2:5], v[52:53], off offset:48
	global_load_dwordx4 v[78:81], v[52:53], off
	global_load_dwordx4 v[82:85], v[52:53], off offset:32
	s_waitcnt vmcnt(5)
	v_lshlrev_b32_e32 v86, 16, v7
	v_and_b32_e32 v88, 0xffff0000, v7
	v_lshlrev_b32_e32 v60, 16, v6
	v_and_b32_e32 v66, 0xffff0000, v6
	v_lshlrev_b32_e32 v92, 16, v9
	v_and_b32_e32 v6, 0xffff0000, v9
	v_lshlrev_b32_e32 v90, 16, v8
	v_and_b32_e32 v8, 0xffff0000, v8
	s_waitcnt vmcnt(4)
	v_lshlrev_b32_e32 v7, 16, v70
	v_and_b32_e32 v9, 0xffff0000, v70
	v_lshlrev_b32_e32 v25, 16, v71
	v_and_b32_e32 v27, 0xffff0000, v71
	v_and_b32_e32 v31, 0xffff0000, v72
	v_cndmask_b32_e64 v61, v7, -v7, s[0:1]
	s_waitcnt vmcnt(1)
	v_mov_b32_e32 v70, v78
	s_waitcnt vmcnt(0)
	v_mov_b32_e32 v71, v82
	v_lshlrev_b32_e32 v33, 16, v73
	v_and_b32_e32 v35, 0xffff0000, v73
	v_pk_mul_f32 v[60:61], v[70:71], v[60:61]
	v_cndmask_b32_e64 v67, v9, -v9, s[0:1]
	v_mov_b32_e32 v82, v79
	v_cndmask_b32_e64 v87, v25, -v25, s[0:1]
	v_mov_b32_e32 v70, v80
	v_mov_b32_e32 v71, v84
	v_cndmask_b32_e64 v89, v27, -v27, s[0:1]
	v_mov_b32_e32 v84, v81
	v_mov_b32_e32 v79, v2
	v_cndmask_b32_e64 v9, v31, -v31, s[0:1]
	v_mov_b32_e32 v2, v75
	v_lshlrev_b32_e32 v29, 16, v72
	v_pk_mul_f32 v[66:67], v[82:83], v[66:67]
	v_pk_mul_f32 v[70:71], v[70:71], v[86:87]
	v_pk_mul_f32 v[72:73], v[84:85], v[88:89]
	v_pk_mul_f32 v[2:3], v[2:3], v[8:9]
	v_cndmask_b32_e64 v93, v33, -v33, s[0:1]
	v_mov_b32_e32 v8, v76
	v_mov_b32_e32 v9, v4
	v_cndmask_b32_e64 v7, v35, -v35, s[0:1]
	v_mov_b32_e32 v4, v77
	v_cndmask_b32_e64 v91, v29, -v29, s[0:1]
	v_mov_b32_e32 v78, v74
	v_pk_mul_f32 v[74:75], v[8:9], v[92:93]
	v_pk_mul_f32 v[4:5], v[4:5], v[6:7]
	v_mov_b32_e32 v6, v60
	v_mov_b32_e32 v7, v66
	v_mov_b32_e32 v66, v61
	v_mov_b32_e32 v8, v70
	v_mov_b32_e32 v9, v72
	v_mov_b32_e32 v72, v71
	v_pk_mul_f32 v[78:79], v[78:79], v[90:91]
	v_pk_add_f32 v[6:7], v[6:7], v[66:67]
	v_pk_add_f32 v[8:9], v[8:9], v[72:73]
	v_cvt_pk_bf16_f32 v6, v6, v7
	v_cvt_pk_bf16_f32 v7, v8, v9
	v_mov_b32_e32 v8, v78
	v_mov_b32_e32 v9, v2
	v_mov_b32_e32 v2, v79
	v_pk_add_f32 v[2:3], v[8:9], v[2:3]
	s_nop 0
	v_cvt_pk_bf16_f32 v8, v2, v3
	v_mov_b32_e32 v2, v74
	v_mov_b32_e32 v3, v4
	v_mov_b32_e32 v4, v75
	v_pk_add_f32 v[2:3], v[2:3], v[4:5]
	s_nop 0
	v_cvt_pk_bf16_f32 v9, v2, v3
; #define LAS __attribute__((address_space(3)))
; #define LDS_WAIT() asm volatile("s_waitcnt lgkmcnt(0)" ::: "memory")
; __device__ __forceinline__ void prep_items(const Ctx& C, int l, int w0, int nw) {
;     ...
;                 for (int q = 0; q < 4; ++q) {
;                     const int r = (lane >> 3) + 8 * q, c = lane & 7;
;                     const bf16_t* row = P + (tokb + r) * PP;
;                     u32x4 kv = *(const u32x4*)(row + kc + 8 * c);
;                     if (c < 2) {
;                         const u32x4 pv = *(const u32x4*)(row + kc + 8 * (c ^ 1));
;                         const float* rt = rope + (tokb + r) * 16;
;                         const f32x4 ca = *(const f32x4*)rt, cb2 = *(const f32x4*)(rt + 4), sa = *(const f32x4*)(rt + 8), sb = *(const f32x4*)(rt + 12);
;                         const float cs[8] = {ca.x, ca.y, ca.z, ca.w, cb2.x, cb2.y, cb2.z, cb2.w}, sn[8] = {sa.x, sa.y, sa.z, sa.w, sb.x, sb.y, sb.z, sb.w};
;                         const float mv[8] = {bf_lo(kv.x), bf_hi(kv.x), bf_lo(kv.y), bf_hi(kv.y), bf_lo(kv.z), bf_hi(kv.z), bf_lo(kv.w), bf_hi(kv.w)};
;                         const float pp[8] = {bf_lo(pv.x), bf_hi(pv.x), bf_lo(pv.y), bf_hi(pv.y), bf_lo(pv.z), bf_hi(pv.z), bf_lo(pv.w), bf_hi(pv.w)};
;                         const float sg = (c == 0) ? -1.f : 1.f; float o[8];
; #pragma unroll
;                         for (int e = 0; e < 8; ++e) o[e] = mv[e] * cs[e] + sg * pp[e] * sn[e];
;                         kv.x = cvt_pk_bf16(o[0], o[1]); kv.y = cvt_pk_bf16(o[2], o[3]); kv.z = cvt_pk_bf16(o[4], o[5]); kv.w = cvt_pk_bf16(o[6], o[7]);
;                     }
;                     if (which == 0)
;                         *(u32x4*)(kop + ((size_t)(((bg * 512 + tile) * 2 + ((r >> 2) & 1)) * 2 + (c >> 2)) * 64 + ((r >> 3) * 4 + (r & 3)) + 16 * (c & 3)) * 8) = kv;
;                     else
;                         *(u32x4*)(kop + ((size_t)((bg * 512 + tile) * 4 + (c >> 1)) * 64 + pi32(r) + 32 * (c & 1)) * 8) = kv;
;                     const u32x4 vv = *(const u32x4*)(row + vc + 8 * c);
;                     *(LAS u32x4*)(vt + r * 72 + 8 * c) = vv;
;                 }
;                 LDS_WAIT();
; #pragma unroll
;                 for (int o4 = 0; o4 < 4; ++o4) {
;                     if (which == 0) {
;                         const LAS bf16_t* sp = vt + (8 * (lane >> 4)) * 72 + 16 * o4 + (lane & 15);
.LBB0_492:
	s_or_b64 exec, exec, s[78:79]
	v_or_b32_e32 v2, v64, v28
	v_mov_b32_e32 v3, v65
	v_lshl_add_u64 v[2:3], v[2:3], 4, s[24:25]
	s_waitcnt vmcnt(0)
	global_store_dwordx4 v[2:3], v[6:9], off
	v_or_b32_e32 v60, s12, v30
	v_mov_b32_e32 v61, s13
	ds_write_b128 v23, v[102:105] offset:2304
	v_mov_b64_e32 v[2:3], s[18:19]
	v_mad_u64_u32 v[2:3], s[2:3], v60, s67, v[2:3]
	v_add_u32_e32 v3, s74, v3
	v_lshl_add_u64 v[66:67], v[2:3], 0, v[0:1]
	global_load_dwordx4 v[6:9], v[66:67], off
	global_load_dwordx4 v[106:109], v[66:67], off offset:256
	s_and_saveexec_b64 s[2:3], vcc
	s_xor_b64 s[2:3], exec, s[2:3]
	s_or_saveexec_b64 s[18:19], s[2:3]
	v_lshlrev_b64 v[4:5], 6, v[60:61]
	v_lshl_add_u64 v[58:59], s[22:23], 0, v[4:5]
	s_xor_b64 exec, exec, s[18:19]
	s_cbranch_execz .LBB0_496
	v_mov_b32_e32 v47, v1
	v_lshl_add_u64 v[2:3], v[2:3], 0, v[46:47]
	global_load_dwordx4 v[70:73], v[2:3], off
	global_load_dwordx4 v[74:77], v[58:59], off offset:16
	s_nop 0
	global_load_dwordx4 v[2:5], v[58:59], off offset:48
	global_load_dwordx4 v[78:81], v[58:59], off
	global_load_dwordx4 v[82:85], v[58:59], off offset:32
	s_waitcnt vmcnt(5)
	v_lshlrev_b32_e32 v86, 16, v6
	v_and_b32_e32 v88, 0xffff0000, v6
	v_lshlrev_b32_e32 v96, 16, v9
	v_and_b32_e32 v6, 0xffff0000, v9
	v_lshlrev_b32_e32 v90, 16, v7
	v_and_b32_e32 v92, 0xffff0000, v7
	v_lshlrev_b32_e32 v94, 16, v8
	v_and_b32_e32 v8, 0xffff0000, v8
	s_waitcnt vmcnt(4)
	v_and_b32_e32 v9, 0xffff0000, v70
	v_lshlrev_b32_e32 v7, 16, v70
	v_lshlrev_b32_e32 v25, 16, v71
	v_and_b32_e32 v27, 0xffff0000, v71
	v_and_b32_e32 v31, 0xffff0000, v72
	s_waitcnt vmcnt(0)
	v_mov_b32_e32 v71, v82
	v_cndmask_b32_e64 v89, v9, -v9, s[0:1]
	v_mov_b32_e32 v82, v79
	v_lshlrev_b32_e32 v29, 16, v72
	v_lshlrev_b32_e32 v33, 16, v73
	v_and_b32_e32 v35, 0xffff0000, v73
	v_cndmask_b32_e64 v87, v7, -v7, s[0:1]
	v_mov_b32_e32 v70, v78
	v_pk_mul_f32 v[72:73], v[82:83], v[88:89]
	v_cndmask_b32_e64 v91, v25, -v25, s[0:1]
	v_mov_b32_e32 v78, v80
	v_mov_b32_e32 v79, v84
	v_cndmask_b32_e64 v93, v27, -v27, s[0:1]
	v_mov_b32_e32 v84, v81
	v_mov_b32_e32 v83, v2
	v_cndmask_b32_e64 v9, v31, -v31, s[0:1]
	v_mov_b32_e32 v2, v75
	v_pk_mul_f32 v[70:71], v[70:71], v[86:87]
	v_pk_mul_f32 v[78:79], v[78:79], v[90:91]
	v_pk_mul_f32 v[80:81], v[84:85], v[92:93]
	v_pk_mul_f32 v[2:3], v[2:3], v[8:9]
	v_cndmask_b32_e64 v97, v33, -v33, s[0:1]
	v_mov_b32_e32 v8, v76
	v_mov_b32_e32 v9, v4
	v_cndmask_b32_e64 v7, v35, -v35, s[0:1]
	v_mov_b32_e32 v4, v77
	v_cndmask_b32_e64 v95, v29, -v29, s[0:1]
	v_mov_b32_e32 v82, v74
	v_pk_mul_f32 v[74:75], v[8:9], v[96:97]
	v_pk_mul_f32 v[4:5], v[4:5], v[6:7]
	v_mov_b32_e32 v6, v70
	v_mov_b32_e32 v7, v72
	v_mov_b32_e32 v72, v71
	v_mov_b32_e32 v8, v78
	v_mov_b32_e32 v9, v80
	v_mov_b32_e32 v80, v79
	v_pk_mul_f32 v[82:83], v[82:83], v[94:95]
	v_pk_add_f32 v[6:7], v[6:7], v[72:73]
	v_pk_add_f32 v[8:9], v[8:9], v[80:81]
	v_cvt_pk_bf16_f32 v6, v6, v7
	v_cvt_pk_bf16_f32 v7, v8, v9
	v_mov_b32_e32 v8, v82
	v_mov_b32_e32 v9, v2
	v_mov_b32_e32 v2, v83
	v_pk_add_f32 v[2:3], v[8:9], v[2:3]
	s_nop 0
	v_cvt_pk_bf16_f32 v8, v2, v3
	v_mov_b32_e32 v2, v74
	v_mov_b32_e32 v3, v4
	v_mov_b32_e32 v4, v75
	v_pk_add_f32 v[2:3], v[2:3], v[4:5]
	s_nop 0
	v_cvt_pk_bf16_f32 v9, v2, v3
.LBB0_496:
	s_or_b64 exec, exec, s[18:19]
	v_or_b32_e32 v64, v64, v32
	v_lshl_add_u64 v[4:5], v[64:65], 4, s[24:25]
	s_waitcnt vmcnt(0)
	global_store_dwordx4 v[4:5], v[6:9], off
	v_mad_u64_u32 v[2:3], s[2:3], v62, s67, 0
	s_mul_i32 s2, s13, 0x1c00
	s_nop 0
	v_add_u32_e32 v3, s2, v3
	s_add_i32 s2, s6, 0xfffff800
	s_ashr_i32 s3, s2, 31
	s_lshl_b64 s[2:3], s[2:3], 10
	ds_write_b128 v23, v[106:109] offset:3456
	s_waitcnt lgkmcnt(0)
	ds_read_u16 v4, v15 offset:144
	ds_read_u16 v5, v15
	ds_read_u16 v25, v15 offset:32
	s_waitcnt lgkmcnt(1)
	v_lshl_or_b32 v4, v4, 16, v5
	ds_read_u16 v5, v15 offset:288
	ds_read_u16 v6, v15 offset:432
	s_waitcnt lgkmcnt(0)
	v_lshl_or_b32 v5, v6, 16, v5
	ds_read_u16 v6, v15 offset:576
	ds_read_u16 v7, v15 offset:720
	s_waitcnt lgkmcnt(0)
	v_lshl_or_b32 v6, v7, 16, v6
	ds_read_u16 v7, v15 offset:864
	ds_read_u16 v8, v15 offset:1008
	s_waitcnt lgkmcnt(0)
	v_lshl_or_b32 v7, v8, 16, v7
	v_lshl_add_u64 v[8:9], v[42:43], 0, s[2:3]
	global_store_dwordx4 v[8:9], v[4:7], off
	ds_read_u16 v4, v15 offset:176
	ds_read_u16 v5, v15 offset:320
	ds_read_u16 v6, v15 offset:464
	s_add_i32 s2, s6, 0xfffff801
	s_ashr_i32 s3, s2, 31
	s_lshl_b64 s[2:3], s[2:3], 10
	s_waitcnt lgkmcnt(2)
	v_lshl_or_b32 v4, v4, 16, v25
	s_waitcnt lgkmcnt(0)
	v_lshl_or_b32 v5, v6, 16, v5
	ds_read_u16 v6, v15 offset:608
	ds_read_u16 v7, v15 offset:752
	s_waitcnt lgkmcnt(0)
	v_lshl_or_b32 v6, v7, 16, v6
	ds_read_u16 v7, v15 offset:896
	ds_read_u16 v8, v15 offset:1040
	s_waitcnt lgkmcnt(0)
	v_lshl_or_b32 v7, v8, 16, v7
	v_lshl_add_u64 v[8:9], v[42:43], 0, s[2:3]
	global_store_dwordx4 v[8:9], v[4:7], off
	ds_read_u16 v4, v15 offset:208
	ds_read_u16 v5, v15 offset:64
	ds_read_u16 v25, v15 offset:96
	s_add_i32 s2, s6, 0xfffff802
	s_ashr_i32 s3, s2, 31
	s_lshl_b64 s[2:3], s[2:3], 10
	s_waitcnt lgkmcnt(1)
	v_lshl_or_b32 v4, v4, 16, v5
	ds_read_u16 v5, v15 offset:352
	ds_read_u16 v6, v15 offset:496
	s_waitcnt lgkmcnt(0)
	v_lshl_or_b32 v5, v6, 16, v5
	ds_read_u16 v6, v15 offset:640
	ds_read_u16 v7, v15 offset:784
	s_waitcnt lgkmcnt(0)
	v_lshl_or_b32 v6, v7, 16, v6
	ds_read_u16 v7, v15 offset:928
	ds_read_u16 v8, v15 offset:1072
	s_waitcnt lgkmcnt(0)
	v_lshl_or_b32 v7, v8, 16, v7
	v_lshl_add_u64 v[8:9], v[42:43], 0, s[2:3]
	global_store_dwordx4 v[8:9], v[4:7], off
	ds_read_u16 v4, v15 offset:240
	ds_read_u16 v5, v15 offset:384
	ds_read_u16 v6, v15 offset:528
	s_add_i32 s2, s6, 0xfffff803
	s_ashr_i32 s3, s2, 31
	s_lshl_b64 s[2:3], s[2:3], 10
	s_add_u32 s12, s16, 0x1400
	s_waitcnt lgkmcnt(0)
	v_lshl_or_b32 v5, v6, 16, v5
	ds_read_u16 v6, v15 offset:672
	ds_read_u16 v7, v15 offset:816
	v_lshl_or_b32 v4, v4, 16, v25
	s_addc_u32 s13, s17, 0
	v_lshl_add_u64 v[2:3], s[12:13], 0, v[2:3]
	v_lshl_add_u64 v[62:63], v[2:3], 0, v[0:1]
	s_waitcnt lgkmcnt(0)
	v_lshl_or_b32 v6, v7, 16, v6
	ds_read_u16 v7, v15 offset:960
	ds_read_u16 v8, v15 offset:1104
	s_waitcnt lgkmcnt(0)
	v_lshl_or_b32 v7, v8, 16, v7
	v_lshl_add_u64 v[8:9], v[42:43], 0, s[2:3]
	global_store_dwordx4 v[8:9], v[4:7], off
	s_waitcnt lgkmcnt(0)
	global_load_dwordx4 v[6:9], v[62:63], off
	global_load_dwordx4 v[102:105], v[62:63], off offset:256
	s_and_saveexec_b64 s[2:3], vcc
	s_xor_b64 s[2:3], exec, s[2:3]
	s_andn2_saveexec_b64 s[18:19], s[2:3]
	s_cbranch_execz .LBB0_500
; #define LAS __attribute__((address_space(3)))
; __device__ __forceinline__ unsigned cvt_pk_bf16(float lo, float hi) { f32x2_t v = {lo, hi}; bf16x2_t b = __builtin_convertvector(v, bf16x2_t); return __builtin_bit_cast(unsigned, b); }
; __device__ __forceinline__ float bf_lo(unsigned u) { return __uint_as_float(u << 16); }
; __device__ __forceinline__ void prep_items(const Ctx& C, int l, int w0, int nw) {
;     ...
;                 for (int q = 0; q < 4; ++q) {
;                     const int r = (lane >> 3) + 8 * q, c = lane & 7;
;                     const bf16_t* row = P + (tokb + r) * PP;
;                     u32x4 kv = *(const u32x4*)(row + kc + 8 * c);
;                     if (c < 2) {
;                         const u32x4 pv = *(const u32x4*)(row + kc + 8 * (c ^ 1));
;                         const float* rt = rope + (tokb + r) * 16;
;                         const f32x4 ca = *(const f32x4*)rt, cb2 = *(const f32x4*)(rt + 4), sa = *(const f32x4*)(rt + 8), sb = *(const f32x4*)(rt + 12);
;                         const float cs[8] = {ca.x, ca.y, ca.z, ca.w, cb2.x, cb2.y, cb2.z, cb2.w}, sn[8] = {sa.x, sa.y, sa.z, sa.w, sb.x, sb.y, sb.z, sb.w};
;                         const float mv[8] = {bf_lo(kv.x), bf_hi(kv.x), bf_lo(kv.y), bf_hi(kv.y), bf_lo(kv.z), bf_hi(kv.z), bf_lo(kv.w), bf_hi(kv.w)};
;                         const float pp[8] = {bf_lo(pv.x), bf_hi(pv.x), bf_lo(pv.y), bf_hi(pv.y), bf_lo(pv.z), bf_hi(pv.z), bf_lo(pv.w), bf_hi(pv.w)};
;                         const float sg = (c == 0) ? -1.f : 1.f; float o[8];
; #pragma unroll
;                         for (int e = 0; e < 8; ++e) o[e] = mv[e] * cs[e] + sg * pp[e] * sn[e];
;                         kv.x = cvt_pk_bf16(o[0], o[1]); kv.y = cvt_pk_bf16(o[2], o[3]); kv.z = cvt_pk_bf16(o[4], o[5]); kv.w = cvt_pk_bf16(o[6], o[7]);
;                     }
;                     if (which == 0)
;                         *(u32x4*)(kop + ((size_t)(((bg * 512 + tile) * 2 + ((r >> 2) & 1)) * 2 + (c >> 2)) * 64 + ((r >> 3) * 4 + (r & 3)) + 16 * (c & 3)) * 8) = kv;
;                     else
;                         *(u32x4*)(kop + ((size_t)((bg * 512 + tile) * 4 + (c >> 1)) * 64 + pi32(r) + 32 * (c & 1)) * 8) = kv;
;                     const u32x4 vv = *(const u32x4*)(row + vc + 8 * c);
;                     *(LAS u32x4*)(vt + r * 72 + 8 * c) = vv;
;                 }
	v_mov_b32_e32 v47, v1
	v_lshl_add_u64 v[2:3], v[2:3], 0, v[46:47]
	global_load_dwordx4 v[64:67], v[2:3], off
	global_load_dwordx4 v[70:73], v[48:49], off offset:16
	s_nop 0
	global_load_dwordx4 v[2:5], v[48:49], off offset:48
	global_load_dwordx4 v[74:77], v[48:49], off
	global_load_dwordx4 v[78:81], v[48:49], off offset:32
	s_waitcnt vmcnt(5)
	v_lshlrev_b32_e32 v48, 16, v6
	v_and_b32_e32 v82, 0xffff0000, v6
	v_lshlrev_b32_e32 v84, 16, v7
	v_and_b32_e32 v86, 0xffff0000, v7
	v_lshlrev_b32_e32 v90, 16, v9
	v_and_b32_e32 v6, 0xffff0000, v9
	v_lshlrev_b32_e32 v88, 16, v8
	v_and_b32_e32 v8, 0xffff0000, v8
	s_waitcnt vmcnt(4)
	v_lshlrev_b32_e32 v7, 16, v64
	v_and_b32_e32 v9, 0xffff0000, v64
	v_lshlrev_b32_e32 v25, 16, v65
	v_and_b32_e32 v27, 0xffff0000, v65
	v_and_b32_e32 v31, 0xffff0000, v66
	v_lshlrev_b32_e32 v29, 16, v66
	v_lshlrev_b32_e32 v33, 16, v67
	v_and_b32_e32 v35, 0xffff0000, v67
	v_cndmask_b32_e64 v49, v7, -v7, s[0:1]
	s_waitcnt vmcnt(1)
	v_mov_b32_e32 v64, v74
	s_waitcnt vmcnt(0)
	v_mov_b32_e32 v65, v78
	v_cndmask_b32_e64 v83, v9, -v9, s[0:1]
	v_mov_b32_e32 v78, v75
	v_cndmask_b32_e64 v85, v25, -v25, s[0:1]
	v_mov_b32_e32 v66, v76
	v_mov_b32_e32 v67, v80
	v_cndmask_b32_e64 v87, v27, -v27, s[0:1]
	v_mov_b32_e32 v80, v77
	v_mov_b32_e32 v77, v2
	v_cndmask_b32_e64 v9, v31, -v31, s[0:1]
	v_mov_b32_e32 v2, v71
	v_pk_mul_f32 v[48:49], v[64:65], v[48:49]
	v_pk_mul_f32 v[64:65], v[78:79], v[82:83]
	v_pk_mul_f32 v[66:67], v[66:67], v[84:85]
	v_pk_mul_f32 v[74:75], v[80:81], v[86:87]
	v_pk_mul_f32 v[2:3], v[2:3], v[8:9]
	v_cndmask_b32_e64 v91, v33, -v33, s[0:1]
	v_mov_b32_e32 v8, v72
	v_mov_b32_e32 v9, v4
	v_cndmask_b32_e64 v7, v35, -v35, s[0:1]
	v_mov_b32_e32 v4, v73
	v_cndmask_b32_e64 v89, v29, -v29, s[0:1]
	v_mov_b32_e32 v76, v70
	v_pk_mul_f32 v[70:71], v[8:9], v[90:91]
	v_pk_mul_f32 v[4:5], v[4:5], v[6:7]
	v_mov_b32_e32 v6, v48
	v_mov_b32_e32 v7, v64
	v_mov_b32_e32 v64, v49
	v_mov_b32_e32 v8, v66
	v_mov_b32_e32 v9, v74
	v_mov_b32_e32 v74, v67
	v_pk_mul_f32 v[76:77], v[76:77], v[88:89]
	v_pk_add_f32 v[6:7], v[6:7], v[64:65]
	v_pk_add_f32 v[8:9], v[8:9], v[74:75]
	v_cvt_pk_bf16_f32 v6, v6, v7
	v_cvt_pk_bf16_f32 v7, v8, v9
	v_mov_b32_e32 v8, v76
	v_mov_b32_e32 v9, v2
	v_mov_b32_e32 v2, v77
	v_pk_add_f32 v[2:3], v[8:9], v[2:3]
	s_nop 0
	v_cvt_pk_bf16_f32 v8, v2, v3
	v_mov_b32_e32 v2, v70
	v_mov_b32_e32 v3, v4
	v_mov_b32_e32 v4, v71
	v_pk_add_f32 v[2:3], v[2:3], v[4:5]
	s_nop 0
	v_cvt_pk_bf16_f32 v9, v2, v3
.LBB0_500:
	s_or_b64 exec, exec, s[18:19]
	v_add_u32_e32 v4, s6, v21
	v_ashrrev_i32_e32 v5, 31, v4
	v_lshlrev_b64 v[48:49], 6, v[4:5]
	v_or_b32_e32 v48, v48, v16
	v_mad_u64_u32 v[2:3], s[2:3], v54, s67, 0
	v_or_b32_e32 v4, v48, v34
	v_mov_b32_e32 v5, v49
	v_add_u32_e32 v3, s74, v3
	v_lshl_add_u64 v[4:5], v[4:5], 4, s[34:35]
	s_waitcnt vmcnt(0)
	global_store_dwordx4 v[4:5], v[6:9], off
	v_lshl_add_u64 v[2:3], s[12:13], 0, v[2:3]
	v_lshl_add_u64 v[54:55], v[2:3], 0, v[0:1]
	s_nop 0
	global_load_dwordx4 v[6:9], v[54:55], off
	global_load_dwordx4 v[106:109], v[54:55], off offset:256
	ds_write_b128 v23, v[102:105]
	s_and_saveexec_b64 s[2:3], vcc
	s_xor_b64 s[2:3], exec, s[2:3]
	s_andn2_saveexec_b64 s[18:19], s[2:3]
	s_cbranch_execz .LBB0_504
	v_mov_b32_e32 v47, v1
	v_lshl_add_u64 v[2:3], v[2:3], 0, v[46:47]
	global_load_dwordx4 v[62:65], v[2:3], off
	global_load_dwordx4 v[70:73], v[50:51], off offset:16
	s_nop 0
	global_load_dwordx4 v[2:5], v[50:51], off offset:48
	global_load_dwordx4 v[74:77], v[50:51], off
	global_load_dwordx4 v[78:81], v[50:51], off offset:32
	s_waitcnt vmcnt(5)
	v_lshlrev_b32_e32 v50, 16, v6
	v_and_b32_e32 v66, 0xffff0000, v6
	v_lshlrev_b32_e32 v82, 16, v7
	v_and_b32_e32 v84, 0xffff0000, v7
	v_lshlrev_b32_e32 v88, 16, v9
	v_and_b32_e32 v6, 0xffff0000, v9
	v_lshlrev_b32_e32 v86, 16, v8
	v_and_b32_e32 v8, 0xffff0000, v8
	s_waitcnt vmcnt(4)
	v_lshlrev_b32_e32 v7, 16, v62
	v_and_b32_e32 v9, 0xffff0000, v62
	v_lshlrev_b32_e32 v25, 16, v63
	v_and_b32_e32 v27, 0xffff0000, v63
	v_and_b32_e32 v31, 0xffff0000, v64
	v_lshlrev_b32_e32 v29, 16, v64
	v_lshlrev_b32_e32 v33, 16, v65
	v_and_b32_e32 v35, 0xffff0000, v65
	v_cndmask_b32_e64 v51, v7, -v7, s[0:1]
	s_waitcnt vmcnt(1)
	v_mov_b32_e32 v62, v74
	s_waitcnt vmcnt(0)
	v_mov_b32_e32 v63, v78
	v_cndmask_b32_e64 v67, v9, -v9, s[0:1]
	v_mov_b32_e32 v78, v75
	v_cndmask_b32_e64 v83, v25, -v25, s[0:1]
	v_mov_b32_e32 v64, v76
	v_mov_b32_e32 v65, v80
	v_cndmask_b32_e64 v85, v27, -v27, s[0:1]
	v_mov_b32_e32 v80, v77
	v_mov_b32_e32 v75, v2
	v_cndmask_b32_e64 v9, v31, -v31, s[0:1]
	v_mov_b32_e32 v2, v71
	v_pk_mul_f32 v[50:51], v[62:63], v[50:51]
	v_pk_mul_f32 v[62:63], v[78:79], v[66:67]
	v_pk_mul_f32 v[64:65], v[64:65], v[82:83]
	v_pk_mul_f32 v[66:67], v[80:81], v[84:85]
	v_pk_mul_f32 v[2:3], v[2:3], v[8:9]
	v_cndmask_b32_e64 v89, v33, -v33, s[0:1]
	v_mov_b32_e32 v8, v72
	v_mov_b32_e32 v9, v4
	v_cndmask_b32_e64 v7, v35, -v35, s[0:1]
	v_mov_b32_e32 v4, v73
	v_cndmask_b32_e64 v87, v29, -v29, s[0:1]
	v_mov_b32_e32 v74, v70
	v_pk_mul_f32 v[70:71], v[8:9], v[88:89]
	v_pk_mul_f32 v[4:5], v[4:5], v[6:7]
	v_mov_b32_e32 v6, v50
	v_mov_b32_e32 v7, v62
	v_mov_b32_e32 v62, v51
	v_mov_b32_e32 v8, v64
	v_mov_b32_e32 v9, v66
	v_mov_b32_e32 v66, v65
	v_pk_mul_f32 v[74:75], v[74:75], v[86:87]
	v_pk_add_f32 v[6:7], v[6:7], v[62:63]
	v_pk_add_f32 v[8:9], v[8:9], v[66:67]
	v_cvt_pk_bf16_f32 v6, v6, v7
	v_cvt_pk_bf16_f32 v7, v8, v9
	v_mov_b32_e32 v8, v74
	v_mov_b32_e32 v9, v2
	v_mov_b32_e32 v2, v75
	v_pk_add_f32 v[2:3], v[8:9], v[2:3]
	s_nop 0
	v_cvt_pk_bf16_f32 v8, v2, v3
	v_mov_b32_e32 v2, v70
	v_mov_b32_e32 v3, v4
	v_mov_b32_e32 v4, v71
	v_pk_add_f32 v[2:3], v[2:3], v[4:5]
	s_nop 0
	v_cvt_pk_bf16_f32 v9, v2, v3
; #define LAS __attribute__((address_space(3)))
; __device__ __forceinline__ unsigned cvt_pk_bf16(float lo, float hi) { f32x2_t v = {lo, hi}; bf16x2_t b = __builtin_convertvector(v, bf16x2_t); return __builtin_bit_cast(unsigned, b); }
; __device__ __forceinline__ float bf_lo(unsigned u) { return __uint_as_float(u << 16); }
; __device__ __forceinline__ void prep_items(const Ctx& C, int l, int w0, int nw) {
;     ...
;                 for (int q = 0; q < 4; ++q) {
;                     const int r = (lane >> 3) + 8 * q, c = lane & 7;
;                     const bf16_t* row = P + (tokb + r) * PP;
;                     u32x4 kv = *(const u32x4*)(row + kc + 8 * c);
;                     if (c < 2) {
;                         const u32x4 pv = *(const u32x4*)(row + kc + 8 * (c ^ 1));
;                         const float* rt = rope + (tokb + r) * 16;
;                         const f32x4 ca = *(const f32x4*)rt, cb2 = *(const f32x4*)(rt + 4), sa = *(const f32x4*)(rt + 8), sb = *(const f32x4*)(rt + 12);
;                         const float cs[8] = {ca.x, ca.y, ca.z, ca.w, cb2.x, cb2.y, cb2.z, cb2.w}, sn[8] = {sa.x, sa.y, sa.z, sa.w, sb.x, sb.y, sb.z, sb.w};
;                         const float mv[8] = {bf_lo(kv.x), bf_hi(kv.x), bf_lo(kv.y), bf_hi(kv.y), bf_lo(kv.z), bf_hi(kv.z), bf_lo(kv.w), bf_hi(kv.w)};
;                         const float pp[8] = {bf_lo(pv.x), bf_hi(pv.x), bf_lo(pv.y), bf_hi(pv.y), bf_lo(pv.z), bf_hi(pv.z), bf_lo(pv.w), bf_hi(pv.w)};
;                         const float sg = (c == 0) ? -1.f : 1.f; float o[8];
; #pragma unroll
;                         for (int e = 0; e < 8; ++e) o[e] = mv[e] * cs[e] + sg * pp[e] * sn[e];
;                         kv.x = cvt_pk_bf16(o[0], o[1]); kv.y = cvt_pk_bf16(o[2], o[3]); kv.z = cvt_pk_bf16(o[4], o[5]); kv.w = cvt_pk_bf16(o[6], o[7]);
;                     }
;                     if (which == 0)
;                         *(u32x4*)(kop + ((size_t)(((bg * 512 + tile) * 2 + ((r >> 2) & 1)) * 2 + (c >> 2)) * 64 + ((r >> 3) * 4 + (r & 3)) + 16 * (c & 3)) * 8) = kv;
;                     else
;                         *(u32x4*)(kop + ((size_t)((bg * 512 + tile) * 4 + (c >> 1)) * 64 + pi32(r) + 32 * (c & 1)) * 8) = kv;
;                     const u32x4 vv = *(const u32x4*)(row + vc + 8 * c);
;                     *(LAS u32x4*)(vt + r * 72 + 8 * c) = vv;
;                 }
.LBB0_504:
	s_or_b64 exec, exec, s[18:19]
	v_mad_u64_u32 v[2:3], s[2:3], v56, s67, 0
	v_or_b32_e32 v4, v48, v36
	v_mov_b32_e32 v5, v49
	v_add_u32_e32 v3, s74, v3
	v_lshl_add_u64 v[4:5], v[4:5], 4, s[34:35]
	s_waitcnt vmcnt(0)
	global_store_dwordx4 v[4:5], v[6:9], off
	v_lshl_add_u64 v[2:3], s[12:13], 0, v[2:3]
	v_lshl_add_u64 v[56:57], v[2:3], 0, v[0:1]
	global_load_dwordx4 v[6:9], v[56:57], off
	global_load_dwordx4 v[102:105], v[56:57], off offset:256
	ds_write_b128 v23, v[106:109] offset:1152
	s_and_saveexec_b64 s[2:3], vcc
	s_xor_b64 s[2:3], exec, s[2:3]
	s_andn2_saveexec_b64 s[18:19], s[2:3]
	s_cbranch_execz .LBB0_508
	v_mov_b32_e32 v47, v1
	v_lshl_add_u64 v[2:3], v[2:3], 0, v[46:47]
	global_load_dwordx4 v[62:65], v[2:3], off
	global_load_dwordx4 v[70:73], v[52:53], off offset:16
	s_nop 0
	global_load_dwordx4 v[2:5], v[52:53], off offset:48
	global_load_dwordx4 v[74:77], v[52:53], off
	s_nop 0
	global_load_dwordx4 v[50:53], v[52:53], off offset:32
	s_waitcnt vmcnt(5)
	v_lshlrev_b32_e32 v78, 16, v7
	v_and_b32_e32 v80, 0xffff0000, v7
	v_lshlrev_b32_e32 v54, 16, v6
	v_and_b32_e32 v66, 0xffff0000, v6
	v_lshlrev_b32_e32 v84, 16, v9
	v_and_b32_e32 v6, 0xffff0000, v9
	v_lshlrev_b32_e32 v82, 16, v8
	v_and_b32_e32 v8, 0xffff0000, v8
	s_waitcnt vmcnt(4)
	v_lshlrev_b32_e32 v7, 16, v62
	v_and_b32_e32 v9, 0xffff0000, v62
	v_lshlrev_b32_e32 v25, 16, v63
	v_and_b32_e32 v27, 0xffff0000, v63
	v_and_b32_e32 v31, 0xffff0000, v64
	v_cndmask_b32_e64 v55, v7, -v7, s[0:1]
	s_waitcnt vmcnt(1)
	v_mov_b32_e32 v62, v74
	s_waitcnt vmcnt(0)
	v_mov_b32_e32 v63, v50
	v_lshlrev_b32_e32 v33, 16, v65
	v_and_b32_e32 v35, 0xffff0000, v65
	v_pk_mul_f32 v[54:55], v[62:63], v[54:55]
	v_cndmask_b32_e64 v67, v9, -v9, s[0:1]
	v_mov_b32_e32 v50, v75
	v_cndmask_b32_e64 v79, v25, -v25, s[0:1]
	v_mov_b32_e32 v62, v76
	v_mov_b32_e32 v63, v52
	v_cndmask_b32_e64 v81, v27, -v27, s[0:1]
	v_mov_b32_e32 v52, v77
	v_mov_b32_e32 v65, v2
	v_cndmask_b32_e64 v9, v31, -v31, s[0:1]
	v_mov_b32_e32 v2, v71
	v_lshlrev_b32_e32 v29, 16, v64
	v_pk_mul_f32 v[50:51], v[50:51], v[66:67]
	v_pk_mul_f32 v[62:63], v[62:63], v[78:79]
	v_pk_mul_f32 v[52:53], v[52:53], v[80:81]
	v_pk_mul_f32 v[2:3], v[2:3], v[8:9]
	v_cndmask_b32_e64 v85, v33, -v33, s[0:1]
	v_mov_b32_e32 v8, v72
	v_mov_b32_e32 v9, v4
	v_cndmask_b32_e64 v7, v35, -v35, s[0:1]
	v_mov_b32_e32 v4, v73
	v_cndmask_b32_e64 v83, v29, -v29, s[0:1]
	v_mov_b32_e32 v64, v70
	v_pk_mul_f32 v[66:67], v[8:9], v[84:85]
	v_pk_mul_f32 v[4:5], v[4:5], v[6:7]
	v_mov_b32_e32 v6, v54
	v_mov_b32_e32 v7, v50
	v_mov_b32_e32 v50, v55
	v_mov_b32_e32 v8, v62
	v_mov_b32_e32 v9, v52
	v_mov_b32_e32 v52, v63
	v_pk_mul_f32 v[64:65], v[64:65], v[82:83]
	v_pk_add_f32 v[6:7], v[6:7], v[50:51]
	v_pk_add_f32 v[8:9], v[8:9], v[52:53]
	v_cvt_pk_bf16_f32 v6, v6, v7
	v_cvt_pk_bf16_f32 v7, v8, v9
	v_mov_b32_e32 v8, v64
	v_mov_b32_e32 v9, v2
	v_mov_b32_e32 v2, v65
	v_pk_add_f32 v[2:3], v[8:9], v[2:3]
	s_nop 0
	v_cvt_pk_bf16_f32 v8, v2, v3
	v_mov_b32_e32 v2, v66
	v_mov_b32_e32 v3, v4
	v_mov_b32_e32 v4, v67
	v_pk_add_f32 v[2:3], v[2:3], v[4:5]
	s_nop 0
	v_cvt_pk_bf16_f32 v9, v2, v3
; #define LAS __attribute__((address_space(3)))
; __device__ __forceinline__ void memkv_ops(const Ctx& C, int w0, int nw) {
;     const bf16_t* src = (const bf16_t*)(C.ws + WS_MKV); bf16_t* ko = (bf16_t*)(C.ws + WS_MEMK); bf16_t* vo = (bf16_t*)(C.ws + WS_MEMV);
;     for (int e = w0 * 64 + C.lane; e < 512 * 1024; e += nw * 64) {
; __device__ __forceinline__ void prep_items(const Ctx& C, int l, int w0, int nw) {
;     ...
;                 for (int q = 0; q < 4; ++q) {
;                     const int r = (lane >> 3) + 8 * q, c = lane & 7;
;                     const bf16_t* row = P + (tokb + r) * PP;
;                     u32x4 kv = *(const u32x4*)(row + kc + 8 * c);
;                     if (c < 2) {
;                         const u32x4 pv = *(const u32x4*)(row + kc + 8 * (c ^ 1));
;                         const float* rt = rope + (tokb + r) * 16;
;                         const f32x4 ca = *(const f32x4*)rt, cb2 = *(const f32x4*)(rt + 4), sa = *(const f32x4*)(rt + 8), sb = *(const f32x4*)(rt + 12);
;                         const float cs[8] = {ca.x, ca.y, ca.z, ca.w, cb2.x, cb2.y, cb2.z, cb2.w}, sn[8] = {sa.x, sa.y, sa.z, sa.w, sb.x, sb.y, sb.z, sb.w};
;                         const float mv[8] = {bf_lo(kv.x), bf_hi(kv.x), bf_lo(kv.y), bf_hi(kv.y), bf_lo(kv.z), bf_hi(kv.z), bf_lo(kv.w), bf_hi(kv.w)};
;                         const float pp[8] = {bf_lo(pv.x), bf_hi(pv.x), bf_lo(pv.y), bf_hi(pv.y), bf_lo(pv.z), bf_hi(pv.z), bf_lo(pv.w), bf_hi(pv.w)};
;                         const float sg = (c == 0) ? -1.f : 1.f; float o[8];
; #pragma unroll
;                         for (int e = 0; e < 8; ++e) o[e] = mv[e] * cs[e] + sg * pp[e] * sn[e];
;                         kv.x = cvt_pk_bf16(o[0], o[1]); kv.y = cvt_pk_bf16(o[2], o[3]); kv.z = cvt_pk_bf16(o[4], o[5]); kv.w = cvt_pk_bf16(o[6], o[7]);
;                     }
;                     if (which == 0)
;                         *(u32x4*)(kop + ((size_t)(((bg * 512 + tile) * 2 + ((r >> 2) & 1)) * 2 + (c >> 2)) * 64 + ((r >> 3) * 4 + (r & 3)) + 16 * (c & 3)) * 8) = kv;
;                     else
;                         *(u32x4*)(kop + ((size_t)((bg * 512 + tile) * 4 + (c >> 1)) * 64 + pi32(r) + 32 * (c & 1)) * 8) = kv;
;                     const u32x4 vv = *(const u32x4*)(row + vc + 8 * c);
;                     *(LAS u32x4*)(vt + r * 72 + 8 * c) = vv;
;                 }
.LBB0_508:
	s_or_b64 exec, exec, s[18:19]
	v_mad_u64_u32 v[2:3], s[2:3], v60, s67, 0
	v_or_b32_e32 v4, v48, v38
	v_mov_b32_e32 v5, v49
	v_add_u32_e32 v3, s74, v3
	v_lshl_add_u64 v[4:5], v[4:5], 4, s[34:35]
	s_waitcnt vmcnt(0)
	global_store_dwordx4 v[4:5], v[6:9], off
	v_lshl_add_u64 v[2:3], s[12:13], 0, v[2:3]
	v_lshl_add_u64 v[50:51], v[2:3], 0, v[0:1]
	global_load_dwordx4 v[6:9], v[50:51], off
	global_load_dwordx4 v[106:109], v[50:51], off offset:256
	ds_write_b128 v23, v[102:105] offset:2304
	s_and_saveexec_b64 s[2:3], vcc
	s_xor_b64 s[2:3], exec, s[2:3]
	s_andn2_saveexec_b64 s[12:13], s[2:3]
	s_cbranch_execz .LBB0_479
	v_mov_b32_e32 v47, v1
	v_lshl_add_u64 v[2:3], v[2:3], 0, v[46:47]
	global_load_dwordx4 v[52:55], v[2:3], off
	global_load_dwordx4 v[60:63], v[58:59], off offset:16
	s_nop 0
	global_load_dwordx4 v[2:5], v[58:59], off offset:48
	global_load_dwordx4 v[64:67], v[58:59], off
	s_nop 0
	global_load_dwordx4 v[56:59], v[58:59], off offset:32
	s_waitcnt vmcnt(5)
	v_lshlrev_b32_e32 v72, 16, v7
	v_and_b32_e32 v74, 0xffff0000, v7
	v_lshlrev_b32_e32 v46, 16, v6
	v_and_b32_e32 v70, 0xffff0000, v6
	v_lshlrev_b32_e32 v78, 16, v9
	v_and_b32_e32 v6, 0xffff0000, v9
	v_lshlrev_b32_e32 v76, 16, v8
	v_and_b32_e32 v8, 0xffff0000, v8
	s_waitcnt vmcnt(4)
	v_lshlrev_b32_e32 v0, 16, v52
	v_and_b32_e32 v7, 0xffff0000, v52
	v_and_b32_e32 v25, 0xffff0000, v53
	v_lshlrev_b32_e32 v9, 16, v53
	v_and_b32_e32 v29, 0xffff0000, v54
	v_lshlrev_b32_e32 v31, 16, v55
	v_and_b32_e32 v33, 0xffff0000, v55
	v_cndmask_b32_e64 v47, v0, -v0, s[0:1]
	s_waitcnt vmcnt(1)
	v_mov_b32_e32 v52, v64
	s_waitcnt vmcnt(0)
	v_mov_b32_e32 v53, v56
	v_cndmask_b32_e64 v71, v7, -v7, s[0:1]
	v_mov_b32_e32 v56, v65
	v_mov_b32_e32 v55, v58
	v_cndmask_b32_e64 v75, v25, -v25, s[0:1]
	v_mov_b32_e32 v58, v67
	v_lshlrev_b32_e32 v27, 16, v54
	v_pk_mul_f32 v[46:47], v[52:53], v[46:47]
	v_pk_mul_f32 v[52:53], v[56:57], v[70:71]
	v_cndmask_b32_e64 v73, v9, -v9, s[0:1]
	v_mov_b32_e32 v54, v66
	v_pk_mul_f32 v[56:57], v[58:59], v[74:75]
	v_mov_b32_e32 v59, v2
	v_cndmask_b32_e64 v9, v29, -v29, s[0:1]
	v_mov_b32_e32 v2, v61
	v_pk_mul_f32 v[54:55], v[54:55], v[72:73]
	v_pk_mul_f32 v[2:3], v[2:3], v[8:9]
	v_cndmask_b32_e64 v79, v31, -v31, s[0:1]
	v_mov_b32_e32 v8, v62
	v_mov_b32_e32 v9, v4
	v_cndmask_b32_e64 v7, v33, -v33, s[0:1]
	v_mov_b32_e32 v4, v63
	v_cndmask_b32_e64 v77, v27, -v27, s[0:1]
	v_mov_b32_e32 v58, v60
	v_pk_mul_f32 v[60:61], v[8:9], v[78:79]
	v_pk_mul_f32 v[4:5], v[4:5], v[6:7]
	v_mov_b32_e32 v6, v46
	v_mov_b32_e32 v7, v52
	v_mov_b32_e32 v52, v47
	v_mov_b32_e32 v8, v54
	v_mov_b32_e32 v9, v56
	v_mov_b32_e32 v56, v55
	v_pk_mul_f32 v[58:59], v[58:59], v[76:77]
	v_pk_add_f32 v[6:7], v[6:7], v[52:53]
	v_pk_add_f32 v[8:9], v[8:9], v[56:57]
	v_cvt_pk_bf16_f32 v6, v6, v7
	v_cvt_pk_bf16_f32 v7, v8, v9
	v_mov_b32_e32 v8, v58
	v_mov_b32_e32 v9, v2
	v_mov_b32_e32 v2, v59
	v_pk_add_f32 v[2:3], v[8:9], v[2:3]
	s_nop 0
	v_cvt_pk_bf16_f32 v8, v2, v3
	v_mov_b32_e32 v2, v60
	v_mov_b32_e32 v3, v4
	v_mov_b32_e32 v4, v61
	v_pk_add_f32 v[2:3], v[2:3], v[4:5]
	s_nop 0
	v_cvt_pk_bf16_f32 v9, v2, v3
	s_branch .LBB0_479
.LBB0_512:
	s_nop 0
	v_lshl_or_b32 v2, s8, 6, v69
	s_mov_b32 s0, 0x80000
	v_cmp_gt_i32_e32 vcc, s0, v2
	s_and_saveexec_b64 s[0:1], vcc
	s_cbranch_execz .LBB0_519
	v_lshlrev_b32_e32 v0, 1, v13
	v_lshl_add_u64 v[4:5], s[4:5], 0, v[0:1]
	s_mov_b64 s[8:9], 0x3c00000
	v_ashrrev_i32_e32 v3, 31, v2
	s_add_u32 s2, s4, 0x3c80000
	v_lshl_add_u64 v[4:5], v[4:5], 0, s[8:9]
	v_lshl_add_u64 v[6:7], v[2:3], 1, s[4:5]
	s_mov_b64 s[8:9], 0x3800000
	s_addc_u32 s3, s5, 0
	v_lshlrev_b32_e32 v8, 2, v2
	v_lshl_add_u64 v[6:7], v[6:7], 0, s[8:9]
	s_mov_b64 s[8:9], 0
	global_load_ushort v98, v[6:7], off
	v_lshl_add_u64 v[104:105], v[6:7], 0, s[28:29]
	global_load_ushort v99, v[104:105], off
	v_lshl_add_u64 v[104:105], v[104:105], 0, s[28:29]
	global_load_ushort v100, v[104:105], off
	v_lshl_add_u64 v[104:105], v[104:105], 0, s[28:29]
	global_load_ushort v101, v[104:105], off
	v_lshl_add_u64 v[104:105], v[104:105], 0, s[28:29]
	global_load_ushort v102, v[104:105], off
	v_lshl_add_u64 v[104:105], v[104:105], 0, s[28:29]
	global_load_ushort v103, v[104:105], off
	s_waitcnt vmcnt(0)
	s_branch .LBB0_515

; __device__ __forceinline__ int pi32(int r) { return (r & 0x13) | ((r & 4) << 1) | ((r & 8) >> 1); }
; __device__ __forceinline__ void memkv_ops(const Ctx& C, int w0, int nw) {
;     const bf16_t* src = (const bf16_t*)(C.ws + WS_MKV); bf16_t* ko = (bf16_t*)(C.ws + WS_MEMK); bf16_t* vo = (bf16_t*)(C.ws + WS_MEMV);
;     for (int e = w0 * 64 + C.lane; e < 512 * 1024; e += nw * 64) {
;         const int mr = e >> 10, col = e & 1023, kv = col >> 9, hm = (col >> 7) & 3, d = col & 127, b = mr >> 8, m = mr & 255;
;         const bf16_t v = src[e];
;         if (kv == 0) ko[((size_t)((((b * 4 + hm) * 8 + (m >> 5)) * 8 + (d >> 4)) * 64 + pi32(m & 31) + 32 * ((d >> 3) & 1))) * 8 + (d & 7)] = v;
;         else vo[((size_t)((((b * 4 + hm) * 16 + (m >> 4)) * 4 + (d >> 5)) * 64 + (d & 31) + 32 * ((m >> 3) & 1))) * 8 + (m & 7)] = v;
;     }
.LBB0_515:
	v_mov_b32_e32 v3, v98
	v_mov_b32_e32 v98, v99
	v_mov_b32_e32 v99, v100
	v_mov_b32_e32 v100, v101
	v_mov_b32_e32 v101, v102
	v_mov_b32_e32 v102, v103
	v_and_b32_e32 v13, 0x200, v2
	v_bfe_u32 v9, v2, 7, 2
	v_and_b32_e32 v0, 0x7f, v2
	v_ashrrev_i32_e32 v12, 18, v2
	v_bfe_u32 v10, v2, 10, 8
	v_cmp_ne_u32_e32 vcc, 0, v13
	s_and_saveexec_b64 s[10:11], vcc
	s_xor_b64 s[12:13], exec, s[10:11]
	s_cbranch_execz .LBB0_517
	v_lshlrev_b32_e32 v12, 6, v12
	v_lshlrev_b32_e32 v9, 4, v9
	v_lshrrev_b32_e32 v10, 4, v10
	v_lshlrev_b32_e32 v0, 1, v0
	v_or3_b32 v9, v9, v12, v10
	v_and_b32_e32 v0, 0xc0, v0
	v_lshl_or_b32 v0, v9, 8, v0
	v_lshrrev_b32_e32 v9, 8, v2
	v_and_b32_e32 v9, 32, v9
	v_or3_b32 v12, v0, v11, v9
	v_ashrrev_i32_e32 v13, 31, v12
	v_lshrrev_b32_e32 v0, 9, v2
	v_lshl_add_u64 v[12:13], v[12:13], 4, s[2:3]
	v_and_b32_e32 v0, 14, v0
	v_lshl_add_u64 v[12:13], v[12:13], 0, v[0:1]
	global_store_short v[12:13], v3, off
.LBB0_517:
	s_andn2_saveexec_b64 s[12:13], s[12:13]
	s_cbranch_execz .LBB0_514
	v_lshrrev_b32_e32 v13, 10, v2
	v_lshlrev_b32_e32 v12, 5, v12
	v_lshlrev_b32_e32 v9, 3, v9
	v_lshrrev_b32_e32 v10, 5, v10
	v_or3_b32 v9, v9, v12, v10
	v_and_b32_e32 v10, 19, v13
	v_lshlrev_b32_e32 v12, 1, v13
	v_lshrrev_b32_e32 v13, 11, v2
	v_lshlrev_b32_e32 v0, 2, v0
	v_and_b32_e32 v12, 8, v12
	v_and_b32_e32 v14, 32, v8
	v_and_or_b32 v10, v13, 4, v10
	v_lshlrev_b32_e32 v9, 9, v9
	v_and_b32_e32 v0, 0x1c0, v0
	v_or3_b32 v10, v10, v14, v12
	v_or3_b32 v12, v10, v0, v9
	v_ashrrev_i32_e32 v13, 31, v12
	v_lshl_add_u64 v[12:13], v[12:13], 4, v[4:5]
	global_store_short v[12:13], v3, off
	s_branch .LBB0_514

; #define LAS __attribute__((address_space(3)))
; __device__ __forceinline__ void cmp_stage2(const Ctx& C, int l) {
;     ...
;     LAS float* ws2 = (LAS float*)C.lds;
;     for (int e = C.tid; e < 256 * 64 / 4; e += NWAVES * 64) ((LAS f32x4*)ws2)[e] = ((const f32x4*)w2)[e];
;     __syncthreads();
.LBB0_582:
	s_mov_b64 s[16:17], 0x2000
	global_load_dwordx4 v[6:9], v[2:3], off
	v_lshl_add_u64 v[10:11], v[2:3], 0, s[16:17]
	global_load_dwordx4 v[12:15], v[10:11], off
	v_lshl_add_u64 v[10:11], v[10:11], 0, s[16:17]
	global_load_dwordx4 v[16:19], v[10:11], off
	v_lshl_add_u64 v[10:11], v[10:11], 0, s[16:17]
	global_load_dwordx4 v[20:23], v[10:11], off
	v_lshl_add_u64 v[10:11], v[10:11], 0, s[16:17]
	global_load_dwordx4 v[24:27], v[10:11], off
	v_lshl_add_u64 v[10:11], v[10:11], 0, s[16:17]
	global_load_dwordx4 v[28:31], v[10:11], off
	v_lshl_add_u64 v[10:11], v[10:11], 0, s[16:17]
	global_load_dwordx4 v[32:35], v[10:11], off
	v_lshl_add_u64 v[10:11], v[10:11], 0, s[16:17]
	global_load_dwordx4 v[36:39], v[10:11], off
	s_waitcnt vmcnt(7)
	ds_write_b128 v5, v[6:9]
	s_waitcnt vmcnt(6)
	ds_write_b128 v5, v[12:15] offset:8192
	s_waitcnt vmcnt(5)
	ds_write_b128 v5, v[16:19] offset:16384
	s_waitcnt vmcnt(4)
	ds_write_b128 v5, v[20:23] offset:24576
	s_waitcnt vmcnt(3)
	ds_write_b128 v5, v[24:27] offset:32768
	s_waitcnt vmcnt(2)
	ds_write_b128 v5, v[28:31] offset:40960
	s_waitcnt vmcnt(1)
	ds_write_b128 v5, v[32:35] offset:49152
	s_waitcnt vmcnt(0)
	ds_write_b128 v5, v[36:39] offset:57344
